# v19 + nt on the row-major gate loads of the mix GEMM-unit epilogue
# baseline (speedup 1.0000x reference)
.LBB0_1086:
	s_waitcnt vmcnt(0)
	s_mov_b64 s[4:5], -1
	s_and_b64 vcc, exec, s[20:21]
	s_barrier
	s_cbranch_vccz .LBB0_1152
	v_lshrrev_b32_e32 v146, 6, v144
	s_movk_i32 s5, 0x90
	s_nop 0
	v_readfirstlane_b32 s4, v146
	s_mul_i32 s4, s4, 0x2400
	s_add_i32 s4, s4, 32
	v_and_b32_e32 v146, 63, v144
	v_lshrrev_b32_e32 v147, 3, v146
	v_and_b32_e32 v148, 7, v146
	v_lshlrev_b32_e32 v148, 4, v148
	v_mad_u32_u24 v0, v147, s5, v148
	v_add_u32_e32 v0, s4, v0
	v_and_b32_e32 v149, 4, v145
	v_lshlrev_b32_e32 v1, 1, v149
	v_mad_u32_u24 v1, v161, s5, v1
	v_add_u32_e32 v1, s4, v1
	v_and_b32_e32 v150, 0xc0, v144
	v_add_u32_e32 v3, v150, v149
	v_lshlrev_b32_e32 v3, 2, v3
	v_lshl_add_u32 v150, v150, 1, v148
	v_lshrrev_b32_e32 v151, 1, v144
	v_and_b32_e32 v151, 0x80, v151
	v_add_u32_e32 v151, v151, v147
	v_mad_u32_u24 v2, v151, s92, v150
	v_lshl_add_u32 v5, v151, 11, v150
	v_readlane_b32 s70, v254, 8
	v_readlane_b32 s71, v254, 9
	s_mul_i32 s4, s68, 0xa00
	s_lshl_b32 s5, s14, 1
	s_add_u32 s4, s4, s5
	s_add_u32 s70, s70, s4
	s_addc_u32 s71, s71, 0
	s_lshl_b32 s4, s68, 11
	s_lshl_b32 s5, s12, 1
	s_add_u32 s4, s4, s5
	s_add_u32 s72, s46, s4
	s_addc_u32 s73, s47, 0
	s_cmp_lg_u64 s[0:1], 0
	s_cbranch_scc1 .Lgepi_scale
	s_add_u32 s74, s70, 0x0
	s_addc_u32 s75, s71, 0
	global_load_dwordx4 v[146:149], v2, s[74:75] nt
	s_add_u32 s74, s70, 0x5000
	s_addc_u32 s75, s71, 0
	global_load_dwordx4 v[150:153], v2, s[74:75] nt
	s_add_u32 s74, s70, 0xa000
	s_addc_u32 s75, s71, 0
	global_load_dwordx4 v[154:157], v2, s[74:75] nt
	s_add_u32 s74, s70, 0xf000
	s_addc_u32 s75, s71, 0
	global_load_dwordx4 v[158:161], v2, s[74:75] nt
	s_add_u32 s74, s70, 0x14000
	s_addc_u32 s75, s71, 0
	global_load_dwordx4 v[162:165], v2, s[74:75] nt
	s_add_u32 s74, s70, 0x19000
	s_addc_u32 s75, s71, 0
	global_load_dwordx4 v[166:169], v2, s[74:75] nt
	s_add_u32 s74, s70, 0x1e000
	s_addc_u32 s75, s71, 0
	global_load_dwordx4 v[170:173], v2, s[74:75] nt
	s_add_u32 s74, s70, 0x23000
	s_addc_u32 s75, s71, 0
	global_load_dwordx4 v[174:177], v2, s[74:75] nt
	s_add_u32 s74, s70, 0x28000
	s_addc_u32 s75, s71, 0
	global_load_dwordx4 v[178:181], v2, s[74:75] nt
	s_add_u32 s74, s70, 0x2d000
	s_addc_u32 s75, s71, 0
	global_load_dwordx4 v[182:185], v2, s[74:75] nt
	s_add_u32 s74, s70, 0x32000
	s_addc_u32 s75, s71, 0
	global_load_dwordx4 v[186:189], v2, s[74:75] nt
	s_add_u32 s74, s70, 0x37000
	s_addc_u32 s75, s71, 0
	global_load_dwordx4 v[190:193], v2, s[74:75] nt
	s_add_u32 s74, s70, 0x3c000
	s_addc_u32 s75, s71, 0
	global_load_dwordx4 v[194:197], v2, s[74:75] nt
	s_add_u32 s74, s70, 0x41000
	s_addc_u32 s75, s71, 0
	global_load_dwordx4 v[198:201], v2, s[74:75] nt
	s_add_u32 s74, s70, 0x46000
	s_addc_u32 s75, s71, 0
	global_load_dwordx4 v[202:205], v2, s[74:75] nt
	s_add_u32 s74, s70, 0x4b000
	s_addc_u32 s75, s71, 0
	global_load_dwordx4 v[206:209], v2, s[74:75] nt
	s_waitcnt vmcnt(15)
	ds_write_b128 v0, v[146:149]
	s_waitcnt vmcnt(14)
	ds_write_b128 v0, v[150:153] offset:1152
	s_waitcnt vmcnt(13)
	ds_write_b128 v0, v[154:157] offset:2304
	s_waitcnt vmcnt(12)
	ds_write_b128 v0, v[158:161] offset:3456
	s_waitcnt vmcnt(11)
	ds_write_b128 v0, v[162:165] offset:4608
	s_waitcnt vmcnt(10)
	ds_write_b128 v0, v[166:169] offset:5760
	s_waitcnt vmcnt(9)
	ds_write_b128 v0, v[170:173] offset:6912
	s_waitcnt vmcnt(8)
	ds_write_b128 v0, v[174:177] offset:8064
	s_waitcnt lgkmcnt(7)
	ds_read_b64 v[146:147], v1
	ds_read_b64 v[148:149], v1 offset:16
	ds_read_b64 v[150:151], v1 offset:32
	ds_read_b64 v[152:153], v1 offset:48
	ds_read_b64 v[154:155], v1 offset:64
	ds_read_b64 v[156:157], v1 offset:80
	ds_read_b64 v[158:159], v1 offset:96
	ds_read_b64 v[160:161], v1 offset:112
	s_waitcnt lgkmcnt(7)
	v_and_b32_e32 v3, 0xffff0000, v146
	v_lshlrev_b32_e32 v2, 16, v146
	v_pk_mul_f32 v[118:119], v[118:119], v[2:3]
	v_and_b32_e32 v3, 0xffff0000, v147
	v_lshlrev_b32_e32 v2, 16, v147
	v_pk_mul_f32 v[120:121], v[120:121], v[2:3]
	v_cvt_pk_bf16_f32 v146, v118, v119
	v_cvt_pk_bf16_f32 v147, v120, v121
	ds_write_b64 v1, v[146:147]
	s_waitcnt lgkmcnt(7)
	v_and_b32_e32 v3, 0xffff0000, v148
	v_lshlrev_b32_e32 v2, 16, v148
	v_pk_mul_f32 v[122:123], v[122:123], v[2:3]
	v_and_b32_e32 v3, 0xffff0000, v149
	v_lshlrev_b32_e32 v2, 16, v149
	v_pk_mul_f32 v[124:125], v[124:125], v[2:3]
	v_cvt_pk_bf16_f32 v148, v122, v123
	v_cvt_pk_bf16_f32 v149, v124, v125
	ds_write_b64 v1, v[148:149] offset:16
	s_waitcnt lgkmcnt(7)
	v_and_b32_e32 v3, 0xffff0000, v150
	v_lshlrev_b32_e32 v2, 16, v150
	v_pk_mul_f32 v[126:127], v[126:127], v[2:3]
	v_and_b32_e32 v3, 0xffff0000, v151
	v_lshlrev_b32_e32 v2, 16, v151
	v_pk_mul_f32 v[128:129], v[128:129], v[2:3]
	v_cvt_pk_bf16_f32 v150, v126, v127
	v_cvt_pk_bf16_f32 v151, v128, v129
	ds_write_b64 v1, v[150:151] offset:32
	s_waitcnt lgkmcnt(7)
	v_and_b32_e32 v3, 0xffff0000, v152
	v_lshlrev_b32_e32 v2, 16, v152
	v_pk_mul_f32 v[130:131], v[130:131], v[2:3]
	v_and_b32_e32 v3, 0xffff0000, v153
	v_lshlrev_b32_e32 v2, 16, v153
	v_pk_mul_f32 v[132:133], v[132:133], v[2:3]
	v_cvt_pk_bf16_f32 v152, v130, v131
	v_cvt_pk_bf16_f32 v153, v132, v133
	ds_write_b64 v1, v[152:153] offset:48
	s_waitcnt lgkmcnt(7)
	v_and_b32_e32 v3, 0xffff0000, v154
	v_lshlrev_b32_e32 v2, 16, v154
	v_pk_mul_f32 v[102:103], v[102:103], v[2:3]
	v_and_b32_e32 v3, 0xffff0000, v155
	v_lshlrev_b32_e32 v2, 16, v155
	v_pk_mul_f32 v[104:105], v[104:105], v[2:3]
	v_cvt_pk_bf16_f32 v154, v102, v103
	v_cvt_pk_bf16_f32 v155, v104, v105
	ds_write_b64 v1, v[154:155] offset:64
	s_waitcnt lgkmcnt(7)
	v_and_b32_e32 v3, 0xffff0000, v156
	v_lshlrev_b32_e32 v2, 16, v156
	v_pk_mul_f32 v[106:107], v[106:107], v[2:3]
	v_and_b32_e32 v3, 0xffff0000, v157
	v_lshlrev_b32_e32 v2, 16, v157
	v_pk_mul_f32 v[108:109], v[108:109], v[2:3]
	v_cvt_pk_bf16_f32 v156, v106, v107
	v_cvt_pk_bf16_f32 v157, v108, v109
	ds_write_b64 v1, v[156:157] offset:80
	s_waitcnt lgkmcnt(7)
	v_and_b32_e32 v3, 0xffff0000, v158
	v_lshlrev_b32_e32 v2, 16, v158
	v_pk_mul_f32 v[110:111], v[110:111], v[2:3]
	v_and_b32_e32 v3, 0xffff0000, v159
	v_lshlrev_b32_e32 v2, 16, v159
	v_pk_mul_f32 v[112:113], v[112:113], v[2:3]
	v_cvt_pk_bf16_f32 v158, v110, v111
	v_cvt_pk_bf16_f32 v159, v112, v113
	ds_write_b64 v1, v[158:159] offset:96
	s_waitcnt lgkmcnt(7)
	v_and_b32_e32 v3, 0xffff0000, v160
	v_lshlrev_b32_e32 v2, 16, v160
	v_pk_mul_f32 v[114:115], v[114:115], v[2:3]
	v_and_b32_e32 v3, 0xffff0000, v161
	v_lshlrev_b32_e32 v2, 16, v161
	v_pk_mul_f32 v[116:117], v[116:117], v[2:3]
	v_cvt_pk_bf16_f32 v160, v114, v115
	v_cvt_pk_bf16_f32 v161, v116, v117
	ds_write_b64 v1, v[160:161] offset:112
	s_waitcnt lgkmcnt(7)
	ds_read_b64 v[162:163], v1 offset:4608
	ds_read_b64 v[164:165], v1 offset:4624
	ds_read_b64 v[166:167], v1 offset:4640
	ds_read_b64 v[168:169], v1 offset:4656
	ds_read_b64 v[170:171], v1 offset:4672
	ds_read_b64 v[172:173], v1 offset:4688
	ds_read_b64 v[174:175], v1 offset:4704
	ds_read_b64 v[176:177], v1 offset:4720
	s_waitcnt lgkmcnt(7)
	v_and_b32_e32 v3, 0xffff0000, v162
	v_lshlrev_b32_e32 v2, 16, v162
	v_pk_mul_f32 v[86:87], v[86:87], v[2:3]
	v_and_b32_e32 v3, 0xffff0000, v163
	v_lshlrev_b32_e32 v2, 16, v163
	v_pk_mul_f32 v[88:89], v[88:89], v[2:3]
	v_cvt_pk_bf16_f32 v162, v86, v87
	v_cvt_pk_bf16_f32 v163, v88, v89
	ds_write_b64 v1, v[162:163] offset:4608
	s_waitcnt lgkmcnt(7)
	v_and_b32_e32 v3, 0xffff0000, v164
	v_lshlrev_b32_e32 v2, 16, v164
	v_pk_mul_f32 v[90:91], v[90:91], v[2:3]
	v_and_b32_e32 v3, 0xffff0000, v165
	v_lshlrev_b32_e32 v2, 16, v165
	v_pk_mul_f32 v[92:93], v[92:93], v[2:3]
	v_cvt_pk_bf16_f32 v164, v90, v91
	v_cvt_pk_bf16_f32 v165, v92, v93
	ds_write_b64 v1, v[164:165] offset:4624
	s_waitcnt lgkmcnt(7)
	v_and_b32_e32 v3, 0xffff0000, v166
	v_lshlrev_b32_e32 v2, 16, v166
	v_pk_mul_f32 v[94:95], v[94:95], v[2:3]
	v_and_b32_e32 v3, 0xffff0000, v167
	v_lshlrev_b32_e32 v2, 16, v167
	v_pk_mul_f32 v[96:97], v[96:97], v[2:3]
	v_cvt_pk_bf16_f32 v166, v94, v95
	v_cvt_pk_bf16_f32 v167, v96, v97
	ds_write_b64 v1, v[166:167] offset:4640
	s_waitcnt lgkmcnt(7)
	v_and_b32_e32 v3, 0xffff0000, v168
	v_lshlrev_b32_e32 v2, 16, v168
	v_pk_mul_f32 v[98:99], v[98:99], v[2:3]
	v_and_b32_e32 v3, 0xffff0000, v169
	v_lshlrev_b32_e32 v2, 16, v169
	v_pk_mul_f32 v[100:101], v[100:101], v[2:3]
	v_cvt_pk_bf16_f32 v168, v98, v99
	v_cvt_pk_bf16_f32 v169, v100, v101
	ds_write_b64 v1, v[168:169] offset:4656
	s_waitcnt lgkmcnt(7)
	v_and_b32_e32 v3, 0xffff0000, v170
	v_lshlrev_b32_e32 v2, 16, v170
	v_pk_mul_f32 v[70:71], v[70:71], v[2:3]
	v_and_b32_e32 v3, 0xffff0000, v171
	v_lshlrev_b32_e32 v2, 16, v171
	v_pk_mul_f32 v[72:73], v[72:73], v[2:3]
	v_cvt_pk_bf16_f32 v170, v70, v71
	v_cvt_pk_bf16_f32 v171, v72, v73
	ds_write_b64 v1, v[170:171] offset:4672
	s_waitcnt lgkmcnt(7)
	v_and_b32_e32 v3, 0xffff0000, v172
	v_lshlrev_b32_e32 v2, 16, v172
	v_pk_mul_f32 v[74:75], v[74:75], v[2:3]
	v_and_b32_e32 v3, 0xffff0000, v173
	v_lshlrev_b32_e32 v2, 16, v173
	v_pk_mul_f32 v[76:77], v[76:77], v[2:3]
	v_cvt_pk_bf16_f32 v172, v74, v75
	v_cvt_pk_bf16_f32 v173, v76, v77
	ds_write_b64 v1, v[172:173] offset:4688
	s_waitcnt lgkmcnt(7)
	v_and_b32_e32 v3, 0xffff0000, v174
	v_lshlrev_b32_e32 v2, 16, v174
	v_pk_mul_f32 v[78:79], v[78:79], v[2:3]
	v_and_b32_e32 v3, 0xffff0000, v175
	v_lshlrev_b32_e32 v2, 16, v175
	v_pk_mul_f32 v[80:81], v[80:81], v[2:3]
	v_cvt_pk_bf16_f32 v174, v78, v79
	v_cvt_pk_bf16_f32 v175, v80, v81
	ds_write_b64 v1, v[174:175] offset:4704
	s_waitcnt lgkmcnt(7)
	v_and_b32_e32 v3, 0xffff0000, v176
	v_lshlrev_b32_e32 v2, 16, v176
	v_pk_mul_f32 v[82:83], v[82:83], v[2:3]
	v_and_b32_e32 v3, 0xffff0000, v177
	v_lshlrev_b32_e32 v2, 16, v177
	v_pk_mul_f32 v[84:85], v[84:85], v[2:3]
	v_cvt_pk_bf16_f32 v176, v82, v83
	v_cvt_pk_bf16_f32 v177, v84, v85
	ds_write_b64 v1, v[176:177] offset:4720
	s_waitcnt lgkmcnt(7)
	ds_read_b128 v[146:149], v0
	ds_read_b128 v[150:153], v0 offset:1152
	ds_read_b128 v[154:157], v0 offset:2304
	ds_read_b128 v[158:161], v0 offset:3456
	ds_read_b128 v[162:165], v0 offset:4608
	ds_read_b128 v[166:169], v0 offset:5760
	ds_read_b128 v[170:173], v0 offset:6912
	ds_read_b128 v[174:177], v0 offset:8064
	s_add_u32 s74, s72, 0x0
	s_addc_u32 s75, s73, 0
	s_waitcnt lgkmcnt(7)
	global_store_dwordx4 v5, v[146:149], s[74:75]
	s_add_u32 s74, s72, 0x4000
	s_addc_u32 s75, s73, 0
	s_waitcnt lgkmcnt(6)
	global_store_dwordx4 v5, v[150:153], s[74:75]
	s_add_u32 s74, s72, 0x8000
	s_addc_u32 s75, s73, 0
	s_waitcnt lgkmcnt(5)
	global_store_dwordx4 v5, v[154:157], s[74:75]
	s_add_u32 s74, s72, 0xc000
	s_addc_u32 s75, s73, 0
	s_waitcnt lgkmcnt(4)
	global_store_dwordx4 v5, v[158:161], s[74:75]
	s_add_u32 s74, s72, 0x10000
	s_addc_u32 s75, s73, 0
	s_waitcnt lgkmcnt(3)
	global_store_dwordx4 v5, v[162:165], s[74:75]
	s_add_u32 s74, s72, 0x14000
	s_addc_u32 s75, s73, 0
	s_waitcnt lgkmcnt(2)
	global_store_dwordx4 v5, v[166:169], s[74:75]
	s_add_u32 s74, s72, 0x18000
	s_addc_u32 s75, s73, 0
	s_waitcnt lgkmcnt(1)
	global_store_dwordx4 v5, v[170:173], s[74:75]
	s_add_u32 s74, s72, 0x1c000
	s_addc_u32 s75, s73, 0
	s_waitcnt lgkmcnt(0)
	global_store_dwordx4 v5, v[174:177], s[74:75]
	s_waitcnt vmcnt(15)
	ds_write_b128 v0, v[178:181]
	s_waitcnt vmcnt(14)
	ds_write_b128 v0, v[182:185] offset:1152
	s_waitcnt vmcnt(13)
	ds_write_b128 v0, v[186:189] offset:2304
	s_waitcnt vmcnt(12)
	ds_write_b128 v0, v[190:193] offset:3456
	s_waitcnt vmcnt(11)
	ds_write_b128 v0, v[194:197] offset:4608
	s_waitcnt vmcnt(10)
	ds_write_b128 v0, v[198:201] offset:5760
	s_waitcnt vmcnt(9)
	ds_write_b128 v0, v[202:205] offset:6912
	s_waitcnt vmcnt(8)
	ds_write_b128 v0, v[206:209] offset:8064
	s_waitcnt lgkmcnt(7)
	ds_read_b64 v[178:179], v1
	ds_read_b64 v[180:181], v1 offset:16
	ds_read_b64 v[182:183], v1 offset:32
	ds_read_b64 v[184:185], v1 offset:48
	ds_read_b64 v[186:187], v1 offset:64
	ds_read_b64 v[188:189], v1 offset:80
	ds_read_b64 v[190:191], v1 offset:96
	ds_read_b64 v[192:193], v1 offset:112
	s_waitcnt lgkmcnt(7)
	v_and_b32_e32 v3, 0xffff0000, v178
	v_lshlrev_b32_e32 v2, 16, v178
	v_pk_mul_f32 v[54:55], v[54:55], v[2:3]
	v_and_b32_e32 v3, 0xffff0000, v179
	v_lshlrev_b32_e32 v2, 16, v179
	v_pk_mul_f32 v[56:57], v[56:57], v[2:3]
	v_cvt_pk_bf16_f32 v178, v54, v55
	v_cvt_pk_bf16_f32 v179, v56, v57
	ds_write_b64 v1, v[178:179]
	s_waitcnt lgkmcnt(7)
	v_and_b32_e32 v3, 0xffff0000, v180
	v_lshlrev_b32_e32 v2, 16, v180
	v_pk_mul_f32 v[58:59], v[58:59], v[2:3]
	v_and_b32_e32 v3, 0xffff0000, v181
	v_lshlrev_b32_e32 v2, 16, v181
	v_pk_mul_f32 v[60:61], v[60:61], v[2:3]
	v_cvt_pk_bf16_f32 v180, v58, v59
	v_cvt_pk_bf16_f32 v181, v60, v61
	ds_write_b64 v1, v[180:181] offset:16
	s_waitcnt lgkmcnt(7)
	v_and_b32_e32 v3, 0xffff0000, v182
	v_lshlrev_b32_e32 v2, 16, v182
	v_pk_mul_f32 v[62:63], v[62:63], v[2:3]
	v_and_b32_e32 v3, 0xffff0000, v183
	v_lshlrev_b32_e32 v2, 16, v183
	v_pk_mul_f32 v[64:65], v[64:65], v[2:3]
	v_cvt_pk_bf16_f32 v182, v62, v63
	v_cvt_pk_bf16_f32 v183, v64, v65
	ds_write_b64 v1, v[182:183] offset:32
	s_waitcnt lgkmcnt(7)
	v_and_b32_e32 v3, 0xffff0000, v184
	v_lshlrev_b32_e32 v2, 16, v184
	v_pk_mul_f32 v[66:67], v[66:67], v[2:3]
	v_and_b32_e32 v3, 0xffff0000, v185
	v_lshlrev_b32_e32 v2, 16, v185
	v_pk_mul_f32 v[68:69], v[68:69], v[2:3]
	v_cvt_pk_bf16_f32 v184, v66, v67
	v_cvt_pk_bf16_f32 v185, v68, v69
	ds_write_b64 v1, v[184:185] offset:48
	s_waitcnt lgkmcnt(7)
	v_and_b32_e32 v3, 0xffff0000, v186
	v_lshlrev_b32_e32 v2, 16, v186
	v_pk_mul_f32 v[38:39], v[38:39], v[2:3]
	v_and_b32_e32 v3, 0xffff0000, v187
	v_lshlrev_b32_e32 v2, 16, v187
	v_pk_mul_f32 v[40:41], v[40:41], v[2:3]
	v_cvt_pk_bf16_f32 v186, v38, v39
	v_cvt_pk_bf16_f32 v187, v40, v41
	ds_write_b64 v1, v[186:187] offset:64
	s_waitcnt lgkmcnt(7)
	v_and_b32_e32 v3, 0xffff0000, v188
	v_lshlrev_b32_e32 v2, 16, v188
	v_pk_mul_f32 v[42:43], v[42:43], v[2:3]
	v_and_b32_e32 v3, 0xffff0000, v189
	v_lshlrev_b32_e32 v2, 16, v189
	v_pk_mul_f32 v[44:45], v[44:45], v[2:3]
	v_cvt_pk_bf16_f32 v188, v42, v43
	v_cvt_pk_bf16_f32 v189, v44, v45
	ds_write_b64 v1, v[188:189] offset:80
	s_waitcnt lgkmcnt(7)
	v_and_b32_e32 v3, 0xffff0000, v190
	v_lshlrev_b32_e32 v2, 16, v190
	v_pk_mul_f32 v[46:47], v[46:47], v[2:3]
	v_and_b32_e32 v3, 0xffff0000, v191
	v_lshlrev_b32_e32 v2, 16, v191
	v_pk_mul_f32 v[48:49], v[48:49], v[2:3]
	v_cvt_pk_bf16_f32 v190, v46, v47
	v_cvt_pk_bf16_f32 v191, v48, v49
	ds_write_b64 v1, v[190:191] offset:96
	s_waitcnt lgkmcnt(7)
	v_and_b32_e32 v3, 0xffff0000, v192
	v_lshlrev_b32_e32 v2, 16, v192
	v_pk_mul_f32 v[50:51], v[50:51], v[2:3]
	v_and_b32_e32 v3, 0xffff0000, v193
	v_lshlrev_b32_e32 v2, 16, v193
	v_pk_mul_f32 v[52:53], v[52:53], v[2:3]
	v_cvt_pk_bf16_f32 v192, v50, v51
	v_cvt_pk_bf16_f32 v193, v52, v53
	ds_write_b64 v1, v[192:193] offset:112
	s_waitcnt lgkmcnt(7)
	ds_read_b64 v[194:195], v1 offset:4608
	ds_read_b64 v[196:197], v1 offset:4624
	ds_read_b64 v[198:199], v1 offset:4640
	ds_read_b64 v[200:201], v1 offset:4656
	ds_read_b64 v[202:203], v1 offset:4672
	ds_read_b64 v[204:205], v1 offset:4688
	ds_read_b64 v[206:207], v1 offset:4704
	ds_read_b64 v[208:209], v1 offset:4720
	s_waitcnt lgkmcnt(7)
	v_and_b32_e32 v3, 0xffff0000, v194
	v_lshlrev_b32_e32 v2, 16, v194
	v_pk_mul_f32 v[22:23], v[22:23], v[2:3]
	v_and_b32_e32 v3, 0xffff0000, v195
	v_lshlrev_b32_e32 v2, 16, v195
	v_pk_mul_f32 v[24:25], v[24:25], v[2:3]
	v_cvt_pk_bf16_f32 v194, v22, v23
	v_cvt_pk_bf16_f32 v195, v24, v25
	ds_write_b64 v1, v[194:195] offset:4608
	s_waitcnt lgkmcnt(7)
	v_and_b32_e32 v3, 0xffff0000, v196
	v_lshlrev_b32_e32 v2, 16, v196
	v_pk_mul_f32 v[26:27], v[26:27], v[2:3]
	v_and_b32_e32 v3, 0xffff0000, v197
	v_lshlrev_b32_e32 v2, 16, v197
	v_pk_mul_f32 v[28:29], v[28:29], v[2:3]
	v_cvt_pk_bf16_f32 v196, v26, v27
	v_cvt_pk_bf16_f32 v197, v28, v29
	ds_write_b64 v1, v[196:197] offset:4624
	s_waitcnt lgkmcnt(7)
	v_and_b32_e32 v3, 0xffff0000, v198
	v_lshlrev_b32_e32 v2, 16, v198
	v_pk_mul_f32 v[30:31], v[30:31], v[2:3]
	v_and_b32_e32 v3, 0xffff0000, v199
	v_lshlrev_b32_e32 v2, 16, v199
	v_pk_mul_f32 v[32:33], v[32:33], v[2:3]
	v_cvt_pk_bf16_f32 v198, v30, v31
	v_cvt_pk_bf16_f32 v199, v32, v33
	ds_write_b64 v1, v[198:199] offset:4640
	s_waitcnt lgkmcnt(7)
	v_and_b32_e32 v3, 0xffff0000, v200
	v_lshlrev_b32_e32 v2, 16, v200
	v_pk_mul_f32 v[34:35], v[34:35], v[2:3]
	v_and_b32_e32 v3, 0xffff0000, v201
	v_lshlrev_b32_e32 v2, 16, v201
	v_pk_mul_f32 v[36:37], v[36:37], v[2:3]
	v_cvt_pk_bf16_f32 v200, v34, v35
	v_cvt_pk_bf16_f32 v201, v36, v37
	ds_write_b64 v1, v[200:201] offset:4656
	s_waitcnt lgkmcnt(7)
	v_and_b32_e32 v3, 0xffff0000, v202
	v_lshlrev_b32_e32 v2, 16, v202
	v_pk_mul_f32 v[6:7], v[6:7], v[2:3]
	v_and_b32_e32 v3, 0xffff0000, v203
	v_lshlrev_b32_e32 v2, 16, v203
	v_pk_mul_f32 v[8:9], v[8:9], v[2:3]
	v_cvt_pk_bf16_f32 v202, v6, v7
	v_cvt_pk_bf16_f32 v203, v8, v9
	ds_write_b64 v1, v[202:203] offset:4672
	s_waitcnt lgkmcnt(7)
	v_and_b32_e32 v3, 0xffff0000, v204
	v_lshlrev_b32_e32 v2, 16, v204
	v_pk_mul_f32 v[10:11], v[10:11], v[2:3]
	v_and_b32_e32 v3, 0xffff0000, v205
	v_lshlrev_b32_e32 v2, 16, v205
	v_pk_mul_f32 v[12:13], v[12:13], v[2:3]
	v_cvt_pk_bf16_f32 v204, v10, v11
	v_cvt_pk_bf16_f32 v205, v12, v13
	ds_write_b64 v1, v[204:205] offset:4688
	s_waitcnt lgkmcnt(7)
	v_and_b32_e32 v3, 0xffff0000, v206
	v_lshlrev_b32_e32 v2, 16, v206
	v_pk_mul_f32 v[14:15], v[14:15], v[2:3]
	v_and_b32_e32 v3, 0xffff0000, v207
	v_lshlrev_b32_e32 v2, 16, v207
	v_pk_mul_f32 v[16:17], v[16:17], v[2:3]
	v_cvt_pk_bf16_f32 v206, v14, v15
	v_cvt_pk_bf16_f32 v207, v16, v17
	ds_write_b64 v1, v[206:207] offset:4704
	s_waitcnt lgkmcnt(7)
	v_and_b32_e32 v3, 0xffff0000, v208
	v_lshlrev_b32_e32 v2, 16, v208
	v_pk_mul_f32 v[18:19], v[18:19], v[2:3]
	v_and_b32_e32 v3, 0xffff0000, v209
	v_lshlrev_b32_e32 v2, 16, v209
	v_pk_mul_f32 v[20:21], v[20:21], v[2:3]
	v_cvt_pk_bf16_f32 v208, v18, v19
	v_cvt_pk_bf16_f32 v209, v20, v21
	ds_write_b64 v1, v[208:209] offset:4720
	s_waitcnt lgkmcnt(7)
	ds_read_b128 v[178:181], v0
	ds_read_b128 v[182:185], v0 offset:1152
	ds_read_b128 v[186:189], v0 offset:2304
	ds_read_b128 v[190:193], v0 offset:3456
	ds_read_b128 v[194:197], v0 offset:4608
	ds_read_b128 v[198:201], v0 offset:5760
	ds_read_b128 v[202:205], v0 offset:6912
	ds_read_b128 v[206:209], v0 offset:8064
	s_add_u32 s74, s72, 0x20000
	s_addc_u32 s75, s73, 0
	s_waitcnt lgkmcnt(7)
	global_store_dwordx4 v5, v[178:181], s[74:75]
	s_add_u32 s74, s72, 0x24000
	s_addc_u32 s75, s73, 0
	s_waitcnt lgkmcnt(6)
	global_store_dwordx4 v5, v[182:185], s[74:75]
	s_add_u32 s74, s72, 0x28000
	s_addc_u32 s75, s73, 0
	s_waitcnt lgkmcnt(5)
	global_store_dwordx4 v5, v[186:189], s[74:75]
	s_add_u32 s74, s72, 0x2c000
	s_addc_u32 s75, s73, 0
	s_waitcnt lgkmcnt(4)
	global_store_dwordx4 v5, v[190:193], s[74:75]
	s_add_u32 s74, s72, 0x30000
	s_addc_u32 s75, s73, 0
	s_waitcnt lgkmcnt(3)
	global_store_dwordx4 v5, v[194:197], s[74:75]
	s_add_u32 s74, s72, 0x34000
	s_addc_u32 s75, s73, 0
	s_waitcnt lgkmcnt(2)
	global_store_dwordx4 v5, v[198:201], s[74:75]
	s_add_u32 s74, s72, 0x38000
	s_addc_u32 s75, s73, 0
	s_waitcnt lgkmcnt(1)
	global_store_dwordx4 v5, v[202:205], s[74:75]
	s_add_u32 s74, s72, 0x3c000
	s_addc_u32 s75, s73, 0
	s_waitcnt lgkmcnt(0)
	global_store_dwordx4 v5, v[206:209], s[74:75]
	s_branch .Lgepi_done
.Lgepi_scale:
	global_load_dwordx4 v[210:213], v3, s[0:1]
	global_load_dwordx4 v[214:217], v3, s[0:1] offset:32
	global_load_dwordx4 v[218:221], v3, s[0:1] offset:64
	global_load_dwordx4 v[222:225], v3, s[0:1] offset:96
	global_load_dwordx4 v[226:229], v3, s[0:1] offset:128
	global_load_dwordx4 v[230:233], v3, s[0:1] offset:160
	global_load_dwordx4 v[234:237], v3, s[0:1] offset:192
	global_load_dwordx4 v[134:137], v3, s[0:1] offset:224
	s_add_u32 s74, s70, 0x0
	s_addc_u32 s75, s71, 0
	global_load_dwordx4 v[146:149], v2, s[74:75] nt
	s_add_u32 s74, s70, 0x5000
	s_addc_u32 s75, s71, 0
	global_load_dwordx4 v[150:153], v2, s[74:75] nt
	s_add_u32 s74, s70, 0xa000
	s_addc_u32 s75, s71, 0
	global_load_dwordx4 v[154:157], v2, s[74:75] nt
	s_add_u32 s74, s70, 0xf000
	s_addc_u32 s75, s71, 0
	global_load_dwordx4 v[158:161], v2, s[74:75] nt
	s_add_u32 s74, s70, 0x14000
	s_addc_u32 s75, s71, 0
	global_load_dwordx4 v[162:165], v2, s[74:75] nt
	s_add_u32 s74, s70, 0x19000
	s_addc_u32 s75, s71, 0
	global_load_dwordx4 v[166:169], v2, s[74:75] nt
	s_add_u32 s74, s70, 0x1e000
	s_addc_u32 s75, s71, 0
	global_load_dwordx4 v[170:173], v2, s[74:75] nt
	s_add_u32 s74, s70, 0x23000
	s_addc_u32 s75, s71, 0
	global_load_dwordx4 v[174:177], v2, s[74:75] nt
	s_add_u32 s74, s70, 0x28000
	s_addc_u32 s75, s71, 0
	global_load_dwordx4 v[178:181], v2, s[74:75] nt
	s_add_u32 s74, s70, 0x2d000
	s_addc_u32 s75, s71, 0
	global_load_dwordx4 v[182:185], v2, s[74:75] nt
	s_add_u32 s74, s70, 0x32000
	s_addc_u32 s75, s71, 0
	global_load_dwordx4 v[186:189], v2, s[74:75] nt
	s_add_u32 s74, s70, 0x37000
	s_addc_u32 s75, s71, 0
	global_load_dwordx4 v[190:193], v2, s[74:75] nt
	s_add_u32 s74, s70, 0x3c000
	s_addc_u32 s75, s71, 0
	global_load_dwordx4 v[194:197], v2, s[74:75] nt
	s_add_u32 s74, s70, 0x41000
	s_addc_u32 s75, s71, 0
	global_load_dwordx4 v[198:201], v2, s[74:75] nt
	s_add_u32 s74, s70, 0x46000
	s_addc_u32 s75, s71, 0
	global_load_dwordx4 v[202:205], v2, s[74:75] nt
	s_add_u32 s74, s70, 0x4b000
	s_addc_u32 s75, s71, 0
	global_load_dwordx4 v[206:209], v2, s[74:75] nt
	s_waitcnt vmcnt(15)
	ds_write_b128 v0, v[146:149]
	s_waitcnt vmcnt(14)
	ds_write_b128 v0, v[150:153] offset:1152
	s_waitcnt vmcnt(13)
	ds_write_b128 v0, v[154:157] offset:2304
	s_waitcnt vmcnt(12)
	ds_write_b128 v0, v[158:161] offset:3456
	s_waitcnt vmcnt(11)
	ds_write_b128 v0, v[162:165] offset:4608
	s_waitcnt vmcnt(10)
	ds_write_b128 v0, v[166:169] offset:5760
	s_waitcnt vmcnt(9)
	ds_write_b128 v0, v[170:173] offset:6912
	s_waitcnt vmcnt(8)
	ds_write_b128 v0, v[174:177] offset:8064
	s_waitcnt lgkmcnt(7)
	ds_read_b64 v[146:147], v1
	ds_read_b64 v[148:149], v1 offset:16
	ds_read_b64 v[150:151], v1 offset:32
	ds_read_b64 v[152:153], v1 offset:48
	ds_read_b64 v[154:155], v1 offset:64
	ds_read_b64 v[156:157], v1 offset:80
	ds_read_b64 v[158:159], v1 offset:96
	ds_read_b64 v[160:161], v1 offset:112
	s_waitcnt lgkmcnt(7)
	v_pk_mul_f32 v[118:119], v[118:119], v[210:211]
	v_pk_mul_f32 v[120:121], v[120:121], v[212:213]
	v_and_b32_e32 v3, 0xffff0000, v146
	v_lshlrev_b32_e32 v2, 16, v146
	v_pk_mul_f32 v[118:119], v[118:119], v[2:3]
	v_and_b32_e32 v3, 0xffff0000, v147
	v_lshlrev_b32_e32 v2, 16, v147
	v_pk_mul_f32 v[120:121], v[120:121], v[2:3]
	v_cvt_pk_bf16_f32 v146, v118, v119
	v_cvt_pk_bf16_f32 v147, v120, v121
	ds_write_b64 v1, v[146:147]
	s_waitcnt lgkmcnt(7)
	v_pk_mul_f32 v[122:123], v[122:123], v[214:215]
	v_pk_mul_f32 v[124:125], v[124:125], v[216:217]
	v_and_b32_e32 v3, 0xffff0000, v148
	v_lshlrev_b32_e32 v2, 16, v148
	v_pk_mul_f32 v[122:123], v[122:123], v[2:3]
	v_and_b32_e32 v3, 0xffff0000, v149
	v_lshlrev_b32_e32 v2, 16, v149
	v_pk_mul_f32 v[124:125], v[124:125], v[2:3]
	v_cvt_pk_bf16_f32 v148, v122, v123
	v_cvt_pk_bf16_f32 v149, v124, v125
	ds_write_b64 v1, v[148:149] offset:16
	s_waitcnt lgkmcnt(7)
	v_pk_mul_f32 v[126:127], v[126:127], v[218:219]
	v_pk_mul_f32 v[128:129], v[128:129], v[220:221]
	v_and_b32_e32 v3, 0xffff0000, v150
	v_lshlrev_b32_e32 v2, 16, v150
	v_pk_mul_f32 v[126:127], v[126:127], v[2:3]
	v_and_b32_e32 v3, 0xffff0000, v151
	v_lshlrev_b32_e32 v2, 16, v151
	v_pk_mul_f32 v[128:129], v[128:129], v[2:3]
	v_cvt_pk_bf16_f32 v150, v126, v127
	v_cvt_pk_bf16_f32 v151, v128, v129
	ds_write_b64 v1, v[150:151] offset:32
	s_waitcnt lgkmcnt(7)
	v_pk_mul_f32 v[130:131], v[130:131], v[222:223]
	v_pk_mul_f32 v[132:133], v[132:133], v[224:225]
	v_and_b32_e32 v3, 0xffff0000, v152
	v_lshlrev_b32_e32 v2, 16, v152
	v_pk_mul_f32 v[130:131], v[130:131], v[2:3]
	v_and_b32_e32 v3, 0xffff0000, v153
	v_lshlrev_b32_e32 v2, 16, v153
	v_pk_mul_f32 v[132:133], v[132:133], v[2:3]
	v_cvt_pk_bf16_f32 v152, v130, v131
	v_cvt_pk_bf16_f32 v153, v132, v133
	ds_write_b64 v1, v[152:153] offset:48
	s_waitcnt lgkmcnt(7)
	v_pk_mul_f32 v[102:103], v[102:103], v[226:227]
	v_pk_mul_f32 v[104:105], v[104:105], v[228:229]
	v_and_b32_e32 v3, 0xffff0000, v154
	v_lshlrev_b32_e32 v2, 16, v154
	v_pk_mul_f32 v[102:103], v[102:103], v[2:3]
	v_and_b32_e32 v3, 0xffff0000, v155
	v_lshlrev_b32_e32 v2, 16, v155
	v_pk_mul_f32 v[104:105], v[104:105], v[2:3]
	v_cvt_pk_bf16_f32 v154, v102, v103
	v_cvt_pk_bf16_f32 v155, v104, v105
	ds_write_b64 v1, v[154:155] offset:64
	s_waitcnt lgkmcnt(7)
	v_pk_mul_f32 v[106:107], v[106:107], v[230:231]
	v_pk_mul_f32 v[108:109], v[108:109], v[232:233]
	v_and_b32_e32 v3, 0xffff0000, v156
	v_lshlrev_b32_e32 v2, 16, v156
	v_pk_mul_f32 v[106:107], v[106:107], v[2:3]
	v_and_b32_e32 v3, 0xffff0000, v157
	v_lshlrev_b32_e32 v2, 16, v157
	v_pk_mul_f32 v[108:109], v[108:109], v[2:3]
	v_cvt_pk_bf16_f32 v156, v106, v107
	v_cvt_pk_bf16_f32 v157, v108, v109
	ds_write_b64 v1, v[156:157] offset:80
	s_waitcnt lgkmcnt(7)
	v_pk_mul_f32 v[110:111], v[110:111], v[234:235]
	v_pk_mul_f32 v[112:113], v[112:113], v[236:237]
	v_and_b32_e32 v3, 0xffff0000, v158
	v_lshlrev_b32_e32 v2, 16, v158
	v_pk_mul_f32 v[110:111], v[110:111], v[2:3]
	v_and_b32_e32 v3, 0xffff0000, v159
	v_lshlrev_b32_e32 v2, 16, v159
	v_pk_mul_f32 v[112:113], v[112:113], v[2:3]
	v_cvt_pk_bf16_f32 v158, v110, v111
	v_cvt_pk_bf16_f32 v159, v112, v113
	ds_write_b64 v1, v[158:159] offset:96
	s_waitcnt lgkmcnt(7)
	v_pk_mul_f32 v[114:115], v[114:115], v[134:135]
	v_pk_mul_f32 v[116:117], v[116:117], v[136:137]
	v_and_b32_e32 v3, 0xffff0000, v160
	v_lshlrev_b32_e32 v2, 16, v160
	v_pk_mul_f32 v[114:115], v[114:115], v[2:3]
	v_and_b32_e32 v3, 0xffff0000, v161
	v_lshlrev_b32_e32 v2, 16, v161
	v_pk_mul_f32 v[116:117], v[116:117], v[2:3]
	v_cvt_pk_bf16_f32 v160, v114, v115
	v_cvt_pk_bf16_f32 v161, v116, v117
	ds_write_b64 v1, v[160:161] offset:112
	s_waitcnt lgkmcnt(7)
	ds_read_b64 v[162:163], v1 offset:4608
	ds_read_b64 v[164:165], v1 offset:4624
	ds_read_b64 v[166:167], v1 offset:4640
	ds_read_b64 v[168:169], v1 offset:4656
	ds_read_b64 v[170:171], v1 offset:4672
	ds_read_b64 v[172:173], v1 offset:4688
	ds_read_b64 v[174:175], v1 offset:4704
	ds_read_b64 v[176:177], v1 offset:4720
	s_waitcnt lgkmcnt(7)
	v_pk_mul_f32 v[86:87], v[86:87], v[210:211]
	v_pk_mul_f32 v[88:89], v[88:89], v[212:213]
	v_and_b32_e32 v3, 0xffff0000, v162
	v_lshlrev_b32_e32 v2, 16, v162
	v_pk_mul_f32 v[86:87], v[86:87], v[2:3]
	v_and_b32_e32 v3, 0xffff0000, v163
	v_lshlrev_b32_e32 v2, 16, v163
	v_pk_mul_f32 v[88:89], v[88:89], v[2:3]
	v_cvt_pk_bf16_f32 v162, v86, v87
	v_cvt_pk_bf16_f32 v163, v88, v89
	ds_write_b64 v1, v[162:163] offset:4608
	s_waitcnt lgkmcnt(7)
	v_pk_mul_f32 v[90:91], v[90:91], v[214:215]
	v_pk_mul_f32 v[92:93], v[92:93], v[216:217]
	v_and_b32_e32 v3, 0xffff0000, v164
	v_lshlrev_b32_e32 v2, 16, v164
	v_pk_mul_f32 v[90:91], v[90:91], v[2:3]
	v_and_b32_e32 v3, 0xffff0000, v165
	v_lshlrev_b32_e32 v2, 16, v165
	v_pk_mul_f32 v[92:93], v[92:93], v[2:3]
	v_cvt_pk_bf16_f32 v164, v90, v91
	v_cvt_pk_bf16_f32 v165, v92, v93
	ds_write_b64 v1, v[164:165] offset:4624
	s_waitcnt lgkmcnt(7)
	v_pk_mul_f32 v[94:95], v[94:95], v[218:219]
	v_pk_mul_f32 v[96:97], v[96:97], v[220:221]
	v_and_b32_e32 v3, 0xffff0000, v166
	v_lshlrev_b32_e32 v2, 16, v166
	v_pk_mul_f32 v[94:95], v[94:95], v[2:3]
	v_and_b32_e32 v3, 0xffff0000, v167
	v_lshlrev_b32_e32 v2, 16, v167
	v_pk_mul_f32 v[96:97], v[96:97], v[2:3]
	v_cvt_pk_bf16_f32 v166, v94, v95
	v_cvt_pk_bf16_f32 v167, v96, v97
	ds_write_b64 v1, v[166:167] offset:4640
	s_waitcnt lgkmcnt(7)
	v_pk_mul_f32 v[98:99], v[98:99], v[222:223]
	v_pk_mul_f32 v[100:101], v[100:101], v[224:225]
	v_and_b32_e32 v3, 0xffff0000, v168
	v_lshlrev_b32_e32 v2, 16, v168
	v_pk_mul_f32 v[98:99], v[98:99], v[2:3]
	v_and_b32_e32 v3, 0xffff0000, v169
	v_lshlrev_b32_e32 v2, 16, v169
	v_pk_mul_f32 v[100:101], v[100:101], v[2:3]
	v_cvt_pk_bf16_f32 v168, v98, v99
	v_cvt_pk_bf16_f32 v169, v100, v101
	ds_write_b64 v1, v[168:169] offset:4656
	s_waitcnt lgkmcnt(7)
	v_pk_mul_f32 v[70:71], v[70:71], v[226:227]
	v_pk_mul_f32 v[72:73], v[72:73], v[228:229]
	v_and_b32_e32 v3, 0xffff0000, v170
	v_lshlrev_b32_e32 v2, 16, v170
	v_pk_mul_f32 v[70:71], v[70:71], v[2:3]
	v_and_b32_e32 v3, 0xffff0000, v171
	v_lshlrev_b32_e32 v2, 16, v171
	v_pk_mul_f32 v[72:73], v[72:73], v[2:3]
	v_cvt_pk_bf16_f32 v170, v70, v71
	v_cvt_pk_bf16_f32 v171, v72, v73
	ds_write_b64 v1, v[170:171] offset:4672
	s_waitcnt lgkmcnt(7)
	v_pk_mul_f32 v[74:75], v[74:75], v[230:231]
	v_pk_mul_f32 v[76:77], v[76:77], v[232:233]
	v_and_b32_e32 v3, 0xffff0000, v172
	v_lshlrev_b32_e32 v2, 16, v172
	v_pk_mul_f32 v[74:75], v[74:75], v[2:3]
	v_and_b32_e32 v3, 0xffff0000, v173
	v_lshlrev_b32_e32 v2, 16, v173
	v_pk_mul_f32 v[76:77], v[76:77], v[2:3]
	v_cvt_pk_bf16_f32 v172, v74, v75
	v_cvt_pk_bf16_f32 v173, v76, v77
	ds_write_b64 v1, v[172:173] offset:4688
	s_waitcnt lgkmcnt(7)
	v_pk_mul_f32 v[78:79], v[78:79], v[234:235]
	v_pk_mul_f32 v[80:81], v[80:81], v[236:237]
	v_and_b32_e32 v3, 0xffff0000, v174
	v_lshlrev_b32_e32 v2, 16, v174
	v_pk_mul_f32 v[78:79], v[78:79], v[2:3]
	v_and_b32_e32 v3, 0xffff0000, v175
	v_lshlrev_b32_e32 v2, 16, v175
	v_pk_mul_f32 v[80:81], v[80:81], v[2:3]
	v_cvt_pk_bf16_f32 v174, v78, v79
	v_cvt_pk_bf16_f32 v175, v80, v81
	ds_write_b64 v1, v[174:175] offset:4704
	s_waitcnt lgkmcnt(7)
	v_pk_mul_f32 v[82:83], v[82:83], v[134:135]
	v_pk_mul_f32 v[84:85], v[84:85], v[136:137]
	v_and_b32_e32 v3, 0xffff0000, v176
	v_lshlrev_b32_e32 v2, 16, v176
	v_pk_mul_f32 v[82:83], v[82:83], v[2:3]
	v_and_b32_e32 v3, 0xffff0000, v177
	v_lshlrev_b32_e32 v2, 16, v177
	v_pk_mul_f32 v[84:85], v[84:85], v[2:3]
	v_cvt_pk_bf16_f32 v176, v82, v83
	v_cvt_pk_bf16_f32 v177, v84, v85
	ds_write_b64 v1, v[176:177] offset:4720
	s_waitcnt lgkmcnt(7)
	ds_read_b128 v[146:149], v0
	ds_read_b128 v[150:153], v0 offset:1152
	ds_read_b128 v[154:157], v0 offset:2304
	ds_read_b128 v[158:161], v0 offset:3456
	ds_read_b128 v[162:165], v0 offset:4608
	ds_read_b128 v[166:169], v0 offset:5760
	ds_read_b128 v[170:173], v0 offset:6912
	ds_read_b128 v[174:177], v0 offset:8064
	s_add_u32 s74, s72, 0x0
	s_addc_u32 s75, s73, 0
	s_waitcnt lgkmcnt(7)
	global_store_dwordx4 v5, v[146:149], s[74:75]
	s_add_u32 s74, s72, 0x4000
	s_addc_u32 s75, s73, 0
	s_waitcnt lgkmcnt(6)
	global_store_dwordx4 v5, v[150:153], s[74:75]
	s_add_u32 s74, s72, 0x8000
	s_addc_u32 s75, s73, 0
	s_waitcnt lgkmcnt(5)
	global_store_dwordx4 v5, v[154:157], s[74:75]
	s_add_u32 s74, s72, 0xc000
	s_addc_u32 s75, s73, 0
	s_waitcnt lgkmcnt(4)
	global_store_dwordx4 v5, v[158:161], s[74:75]
	s_add_u32 s74, s72, 0x10000
	s_addc_u32 s75, s73, 0
	s_waitcnt lgkmcnt(3)
	global_store_dwordx4 v5, v[162:165], s[74:75]
	s_add_u32 s74, s72, 0x14000
	s_addc_u32 s75, s73, 0
	s_waitcnt lgkmcnt(2)
	global_store_dwordx4 v5, v[166:169], s[74:75]
	s_add_u32 s74, s72, 0x18000
	s_addc_u32 s75, s73, 0
	s_waitcnt lgkmcnt(1)
	global_store_dwordx4 v5, v[170:173], s[74:75]
	s_add_u32 s74, s72, 0x1c000
	s_addc_u32 s75, s73, 0
	s_waitcnt lgkmcnt(0)
	global_store_dwordx4 v5, v[174:177], s[74:75]
	s_waitcnt vmcnt(15)
	ds_write_b128 v0, v[178:181]
	s_waitcnt vmcnt(14)
	ds_write_b128 v0, v[182:185] offset:1152
	s_waitcnt vmcnt(13)
	ds_write_b128 v0, v[186:189] offset:2304
	s_waitcnt vmcnt(12)
	ds_write_b128 v0, v[190:193] offset:3456
	s_waitcnt vmcnt(11)
	ds_write_b128 v0, v[194:197] offset:4608
	s_waitcnt vmcnt(10)
	ds_write_b128 v0, v[198:201] offset:5760
	s_waitcnt vmcnt(9)
	ds_write_b128 v0, v[202:205] offset:6912
	s_waitcnt vmcnt(8)
	ds_write_b128 v0, v[206:209] offset:8064
	s_waitcnt lgkmcnt(7)
	ds_read_b64 v[178:179], v1
	ds_read_b64 v[180:181], v1 offset:16
	ds_read_b64 v[182:183], v1 offset:32
	ds_read_b64 v[184:185], v1 offset:48
	ds_read_b64 v[186:187], v1 offset:64
	ds_read_b64 v[188:189], v1 offset:80
	ds_read_b64 v[190:191], v1 offset:96
	ds_read_b64 v[192:193], v1 offset:112
	s_waitcnt lgkmcnt(7)
	v_pk_mul_f32 v[54:55], v[54:55], v[210:211]
	v_pk_mul_f32 v[56:57], v[56:57], v[212:213]
	v_and_b32_e32 v3, 0xffff0000, v178
	v_lshlrev_b32_e32 v2, 16, v178
	v_pk_mul_f32 v[54:55], v[54:55], v[2:3]
	v_and_b32_e32 v3, 0xffff0000, v179
	v_lshlrev_b32_e32 v2, 16, v179
	v_pk_mul_f32 v[56:57], v[56:57], v[2:3]
	v_cvt_pk_bf16_f32 v178, v54, v55
	v_cvt_pk_bf16_f32 v179, v56, v57
	ds_write_b64 v1, v[178:179]
	s_waitcnt lgkmcnt(7)
	v_pk_mul_f32 v[58:59], v[58:59], v[214:215]
	v_pk_mul_f32 v[60:61], v[60:61], v[216:217]
	v_and_b32_e32 v3, 0xffff0000, v180
	v_lshlrev_b32_e32 v2, 16, v180
	v_pk_mul_f32 v[58:59], v[58:59], v[2:3]
	v_and_b32_e32 v3, 0xffff0000, v181
	v_lshlrev_b32_e32 v2, 16, v181
	v_pk_mul_f32 v[60:61], v[60:61], v[2:3]
	v_cvt_pk_bf16_f32 v180, v58, v59
	v_cvt_pk_bf16_f32 v181, v60, v61
	ds_write_b64 v1, v[180:181] offset:16
	s_waitcnt lgkmcnt(7)
	v_pk_mul_f32 v[62:63], v[62:63], v[218:219]
	v_pk_mul_f32 v[64:65], v[64:65], v[220:221]
	v_and_b32_e32 v3, 0xffff0000, v182
	v_lshlrev_b32_e32 v2, 16, v182
	v_pk_mul_f32 v[62:63], v[62:63], v[2:3]
	v_and_b32_e32 v3, 0xffff0000, v183
	v_lshlrev_b32_e32 v2, 16, v183
	v_pk_mul_f32 v[64:65], v[64:65], v[2:3]
	v_cvt_pk_bf16_f32 v182, v62, v63
	v_cvt_pk_bf16_f32 v183, v64, v65
	ds_write_b64 v1, v[182:183] offset:32
	s_waitcnt lgkmcnt(7)
	v_pk_mul_f32 v[66:67], v[66:67], v[222:223]
	v_pk_mul_f32 v[68:69], v[68:69], v[224:225]
	v_and_b32_e32 v3, 0xffff0000, v184
	v_lshlrev_b32_e32 v2, 16, v184
	v_pk_mul_f32 v[66:67], v[66:67], v[2:3]
	v_and_b32_e32 v3, 0xffff0000, v185
	v_lshlrev_b32_e32 v2, 16, v185
	v_pk_mul_f32 v[68:69], v[68:69], v[2:3]
	v_cvt_pk_bf16_f32 v184, v66, v67
	v_cvt_pk_bf16_f32 v185, v68, v69
	ds_write_b64 v1, v[184:185] offset:48
	s_waitcnt lgkmcnt(7)
	v_pk_mul_f32 v[38:39], v[38:39], v[226:227]
	v_pk_mul_f32 v[40:41], v[40:41], v[228:229]
	v_and_b32_e32 v3, 0xffff0000, v186
	v_lshlrev_b32_e32 v2, 16, v186
	v_pk_mul_f32 v[38:39], v[38:39], v[2:3]
	v_and_b32_e32 v3, 0xffff0000, v187
	v_lshlrev_b32_e32 v2, 16, v187
	v_pk_mul_f32 v[40:41], v[40:41], v[2:3]
	v_cvt_pk_bf16_f32 v186, v38, v39
	v_cvt_pk_bf16_f32 v187, v40, v41
	ds_write_b64 v1, v[186:187] offset:64
	s_waitcnt lgkmcnt(7)
	v_pk_mul_f32 v[42:43], v[42:43], v[230:231]
	v_pk_mul_f32 v[44:45], v[44:45], v[232:233]
	v_and_b32_e32 v3, 0xffff0000, v188
	v_lshlrev_b32_e32 v2, 16, v188
	v_pk_mul_f32 v[42:43], v[42:43], v[2:3]
	v_and_b32_e32 v3, 0xffff0000, v189
	v_lshlrev_b32_e32 v2, 16, v189
	v_pk_mul_f32 v[44:45], v[44:45], v[2:3]
	v_cvt_pk_bf16_f32 v188, v42, v43
	v_cvt_pk_bf16_f32 v189, v44, v45
	ds_write_b64 v1, v[188:189] offset:80
	s_waitcnt lgkmcnt(7)
	v_pk_mul_f32 v[46:47], v[46:47], v[234:235]
	v_pk_mul_f32 v[48:49], v[48:49], v[236:237]
	v_and_b32_e32 v3, 0xffff0000, v190
	v_lshlrev_b32_e32 v2, 16, v190
	v_pk_mul_f32 v[46:47], v[46:47], v[2:3]
	v_and_b32_e32 v3, 0xffff0000, v191
	v_lshlrev_b32_e32 v2, 16, v191
	v_pk_mul_f32 v[48:49], v[48:49], v[2:3]
	v_cvt_pk_bf16_f32 v190, v46, v47
	v_cvt_pk_bf16_f32 v191, v48, v49
	ds_write_b64 v1, v[190:191] offset:96
	s_waitcnt lgkmcnt(7)
	v_pk_mul_f32 v[50:51], v[50:51], v[134:135]
	v_pk_mul_f32 v[52:53], v[52:53], v[136:137]
	v_and_b32_e32 v3, 0xffff0000, v192
	v_lshlrev_b32_e32 v2, 16, v192
	v_pk_mul_f32 v[50:51], v[50:51], v[2:3]
	v_and_b32_e32 v3, 0xffff0000, v193
	v_lshlrev_b32_e32 v2, 16, v193
	v_pk_mul_f32 v[52:53], v[52:53], v[2:3]
	v_cvt_pk_bf16_f32 v192, v50, v51
	v_cvt_pk_bf16_f32 v193, v52, v53
	ds_write_b64 v1, v[192:193] offset:112
	s_waitcnt lgkmcnt(7)
	ds_read_b64 v[194:195], v1 offset:4608
	ds_read_b64 v[196:197], v1 offset:4624
	ds_read_b64 v[198:199], v1 offset:4640
	ds_read_b64 v[200:201], v1 offset:4656
	ds_read_b64 v[202:203], v1 offset:4672
	ds_read_b64 v[204:205], v1 offset:4688
	ds_read_b64 v[206:207], v1 offset:4704
	ds_read_b64 v[208:209], v1 offset:4720
	s_waitcnt lgkmcnt(7)
	v_pk_mul_f32 v[22:23], v[22:23], v[210:211]
	v_pk_mul_f32 v[24:25], v[24:25], v[212:213]
	v_and_b32_e32 v3, 0xffff0000, v194
	v_lshlrev_b32_e32 v2, 16, v194
	v_pk_mul_f32 v[22:23], v[22:23], v[2:3]
	v_and_b32_e32 v3, 0xffff0000, v195
	v_lshlrev_b32_e32 v2, 16, v195
	v_pk_mul_f32 v[24:25], v[24:25], v[2:3]
	v_cvt_pk_bf16_f32 v194, v22, v23
	v_cvt_pk_bf16_f32 v195, v24, v25
	ds_write_b64 v1, v[194:195] offset:4608
	s_waitcnt lgkmcnt(7)
	v_pk_mul_f32 v[26:27], v[26:27], v[214:215]
	v_pk_mul_f32 v[28:29], v[28:29], v[216:217]
	v_and_b32_e32 v3, 0xffff0000, v196
	v_lshlrev_b32_e32 v2, 16, v196
	v_pk_mul_f32 v[26:27], v[26:27], v[2:3]
	v_and_b32_e32 v3, 0xffff0000, v197
	v_lshlrev_b32_e32 v2, 16, v197
	v_pk_mul_f32 v[28:29], v[28:29], v[2:3]
	v_cvt_pk_bf16_f32 v196, v26, v27
	v_cvt_pk_bf16_f32 v197, v28, v29
	ds_write_b64 v1, v[196:197] offset:4624
	s_waitcnt lgkmcnt(7)
	v_pk_mul_f32 v[30:31], v[30:31], v[218:219]
	v_pk_mul_f32 v[32:33], v[32:33], v[220:221]
	v_and_b32_e32 v3, 0xffff0000, v198
	v_lshlrev_b32_e32 v2, 16, v198
	v_pk_mul_f32 v[30:31], v[30:31], v[2:3]
	v_and_b32_e32 v3, 0xffff0000, v199
	v_lshlrev_b32_e32 v2, 16, v199
	v_pk_mul_f32 v[32:33], v[32:33], v[2:3]
	v_cvt_pk_bf16_f32 v198, v30, v31
	v_cvt_pk_bf16_f32 v199, v32, v33
	ds_write_b64 v1, v[198:199] offset:4640
	s_waitcnt lgkmcnt(7)
	v_pk_mul_f32 v[34:35], v[34:35], v[222:223]
	v_pk_mul_f32 v[36:37], v[36:37], v[224:225]
	v_and_b32_e32 v3, 0xffff0000, v200
	v_lshlrev_b32_e32 v2, 16, v200
	v_pk_mul_f32 v[34:35], v[34:35], v[2:3]
	v_and_b32_e32 v3, 0xffff0000, v201
	v_lshlrev_b32_e32 v2, 16, v201
	v_pk_mul_f32 v[36:37], v[36:37], v[2:3]
	v_cvt_pk_bf16_f32 v200, v34, v35
	v_cvt_pk_bf16_f32 v201, v36, v37
	ds_write_b64 v1, v[200:201] offset:4656
	s_waitcnt lgkmcnt(7)
	v_pk_mul_f32 v[6:7], v[6:7], v[226:227]
	v_pk_mul_f32 v[8:9], v[8:9], v[228:229]
	v_and_b32_e32 v3, 0xffff0000, v202
	v_lshlrev_b32_e32 v2, 16, v202
	v_pk_mul_f32 v[6:7], v[6:7], v[2:3]
	v_and_b32_e32 v3, 0xffff0000, v203
	v_lshlrev_b32_e32 v2, 16, v203
	v_pk_mul_f32 v[8:9], v[8:9], v[2:3]
	v_cvt_pk_bf16_f32 v202, v6, v7
	v_cvt_pk_bf16_f32 v203, v8, v9
	ds_write_b64 v1, v[202:203] offset:4672
	s_waitcnt lgkmcnt(7)
	v_pk_mul_f32 v[10:11], v[10:11], v[230:231]
	v_pk_mul_f32 v[12:13], v[12:13], v[232:233]
	v_and_b32_e32 v3, 0xffff0000, v204
	v_lshlrev_b32_e32 v2, 16, v204
	v_pk_mul_f32 v[10:11], v[10:11], v[2:3]
	v_and_b32_e32 v3, 0xffff0000, v205
	v_lshlrev_b32_e32 v2, 16, v205
	v_pk_mul_f32 v[12:13], v[12:13], v[2:3]
	v_cvt_pk_bf16_f32 v204, v10, v11
	v_cvt_pk_bf16_f32 v205, v12, v13
	ds_write_b64 v1, v[204:205] offset:4688
	s_waitcnt lgkmcnt(7)
	v_pk_mul_f32 v[14:15], v[14:15], v[234:235]
	v_pk_mul_f32 v[16:17], v[16:17], v[236:237]
	v_and_b32_e32 v3, 0xffff0000, v206
	v_lshlrev_b32_e32 v2, 16, v206
	v_pk_mul_f32 v[14:15], v[14:15], v[2:3]
	v_and_b32_e32 v3, 0xffff0000, v207
	v_lshlrev_b32_e32 v2, 16, v207
	v_pk_mul_f32 v[16:17], v[16:17], v[2:3]
	v_cvt_pk_bf16_f32 v206, v14, v15
	v_cvt_pk_bf16_f32 v207, v16, v17
	ds_write_b64 v1, v[206:207] offset:4704
	s_waitcnt lgkmcnt(7)
	v_pk_mul_f32 v[18:19], v[18:19], v[134:135]
	v_pk_mul_f32 v[20:21], v[20:21], v[136:137]
	v_and_b32_e32 v3, 0xffff0000, v208
	v_lshlrev_b32_e32 v2, 16, v208
	v_pk_mul_f32 v[18:19], v[18:19], v[2:3]
	v_and_b32_e32 v3, 0xffff0000, v209
	v_lshlrev_b32_e32 v2, 16, v209
	v_pk_mul_f32 v[20:21], v[20:21], v[2:3]
	v_cvt_pk_bf16_f32 v208, v18, v19
	v_cvt_pk_bf16_f32 v209, v20, v21
	ds_write_b64 v1, v[208:209] offset:4720
	s_waitcnt lgkmcnt(7)
	ds_read_b128 v[178:181], v0
	ds_read_b128 v[182:185], v0 offset:1152
	ds_read_b128 v[186:189], v0 offset:2304
	ds_read_b128 v[190:193], v0 offset:3456
	ds_read_b128 v[194:197], v0 offset:4608
	ds_read_b128 v[198:201], v0 offset:5760
	ds_read_b128 v[202:205], v0 offset:6912
	ds_read_b128 v[206:209], v0 offset:8064
	s_add_u32 s74, s72, 0x20000
	s_addc_u32 s75, s73, 0
	s_waitcnt lgkmcnt(7)
	global_store_dwordx4 v5, v[178:181], s[74:75]
	s_add_u32 s74, s72, 0x24000
	s_addc_u32 s75, s73, 0
	s_waitcnt lgkmcnt(6)
	global_store_dwordx4 v5, v[182:185], s[74:75]
	s_add_u32 s74, s72, 0x28000
	s_addc_u32 s75, s73, 0
	s_waitcnt lgkmcnt(5)
	global_store_dwordx4 v5, v[186:189], s[74:75]
	s_add_u32 s74, s72, 0x2c000
	s_addc_u32 s75, s73, 0
	s_waitcnt lgkmcnt(4)
	global_store_dwordx4 v5, v[190:193], s[74:75]
	s_add_u32 s74, s72, 0x30000
	s_addc_u32 s75, s73, 0
	s_waitcnt lgkmcnt(3)
	global_store_dwordx4 v5, v[194:197], s[74:75]
	s_add_u32 s74, s72, 0x34000
	s_addc_u32 s75, s73, 0
	s_waitcnt lgkmcnt(2)
	global_store_dwordx4 v5, v[198:201], s[74:75]
	s_add_u32 s74, s72, 0x38000
	s_addc_u32 s75, s73, 0
	s_waitcnt lgkmcnt(1)
	global_store_dwordx4 v5, v[202:205], s[74:75]
	s_add_u32 s74, s72, 0x3c000
	s_addc_u32 s75, s73, 0
	s_waitcnt lgkmcnt(0)
	global_store_dwordx4 v5, v[206:209], s[74:75]
